# item order variant: short differential tile (7-j) first, retention pair, long differential tile (15-j) last
# speedup vs baseline: 1.0087x; 1.0087x over previous
; __device__ __forceinline__ int lane_id() { return (int)__builtin_amdgcn_mbcnt_hi(~0u, __builtin_amdgcn_mbcnt_lo(~0u, 0u)); }
; __global__ void __launch_bounds__(NWAVES * 64, 2) fwd(Args args) {
;     ...
;         unsigned char* wsp = ws; asm volatile("" : "+s"(wsp)); const unsigned char* tbl = wsp + WS_PTRS;
;         const float* ret_gn = ld_uptr(tbl, 4); const float* diff_qn = ld_uptr(tbl, 5); const float* diff_kn = ld_uptr(tbl, 6); const float* lq1 = ld_uptr(tbl, 7); const float* lk1 = ld_uptr(tbl, 8);
;         const float* lq2 = ld_uptr(tbl, 9); const float* lk2 = ld_uptr(tbl, 10); const float* subln = ld_uptr(tbl, 11);
;         bf16_t* Z = (bf16_t*)(wsp + WS_Z); bf16_t* MIX = (bf16_t*)(wsp + WS_MIX);
;         int lane2 = lane_id(); asm volatile("" : "+v"(lane2));
;         const float d1 = wave_sum(lq1[lane2] * lk1[lane2]), d2 = wave_sum(lq2[lane2] * lk2[lane2]);
;         float lam; { float lv = __expf(d1) - __expf(d2) + 0.2f; asm volatile("" : "+v"(lv)); lam = __uint_as_float(__builtin_amdgcn_readfirstlane(__float_as_uint(lv))); }
;         const float mq = wave_max(fabsf(diff_qn[lane2])), mk = wave_max(fabsf(diff_kn[lane2]));
;         float shift; { float sv = 11.541560327111707f * mq * mk; asm volatile("" : "+v"(sv)); shift = __uint_as_float(__builtin_amdgcn_readfirstlane(__float_as_uint(sv))); }
;         for (int pi = vcu; pi < 256; pi += G) {
.LBB0_561:
	s_cmp_lt_i32 s82, 3
	s_cselect_b64 s[2:3], -1, 0
	v_writelane_b32 v254, s2, 2
	s_and_b64 s[0:1], s[2:3], s[0:1]
	s_andn2_b64 vcc, exec, s[0:1]
	v_writelane_b32 v254, s3, 3
	s_cbranch_vccnz .LBB0_654
	v_writelane_b32 v254, s96, 4
	v_mov_b32_e32 v181, 0
	v_mbcnt_lo_u32_b32 v13, -1, 0
	v_writelane_b32 v254, s97, 5
	v_writelane_b32 v254, s94, 6
	v_writelane_b32 v254, s93, 7
	v_writelane_b32 v254, s92, 8
	v_writelane_b32 v254, s90, 9
	v_mbcnt_hi_u32_b32 v183, -1, v13
	v_mov_b32_e32 v12, 0x20000
	v_writelane_b32 v254, s91, 10
	v_writelane_b32 v254, s87, 11
	v_writelane_b32 v254, s88, 12
	v_mov_b32_e32 v16, v183
	s_mov_b32 s27, 0
	v_writelane_b32 v254, s89, 13
	v_writelane_b32 v254, s86, 14
	v_writelane_b32 v254, s84, 15
	s_nop 1
	v_writelane_b32 v254, s85, 16
	v_writelane_b32 v254, s79, 17
	v_writelane_b32 v254, s77, 18
	v_writelane_b32 v254, s80, 19
	s_mov_b64 s[0:1], s[80:81]
	s_add_u32 s2, s0, 0x20020
	s_addc_u32 s3, s1, 0
	global_load_dwordx4 v[0:3], v181, s[2:3] offset:16
	global_load_dwordx4 v[4:7], v181, s[2:3] offset:32
	global_load_dwordx4 v[8:11], v181, s[2:3] offset:48
	v_writelane_b32 v254, s81, 20
	global_load_dwordx4 v[12:15], v12, s[0:1] offset:32
	v_writelane_b32 v254, s82, 21
	v_ashrrev_i32_e32 v17, 31, v16
	v_lshlrev_b64 v[16:17], 2, v[16:17]
	v_writelane_b32 v254, s83, 22
	s_cmpk_gt_i32 s95, 0xff
	s_waitcnt vmcnt(0)
	v_readfirstlane_b32 s3, v3
	v_readfirstlane_b32 s2, v2
	v_readfirstlane_b32 s5, v5
	v_readfirstlane_b32 s4, v4
	v_readfirstlane_b32 s7, v7
	v_readfirstlane_b32 s6, v6
	v_readfirstlane_b32 s9, v9
	v_readfirstlane_b32 s8, v8
	v_lshl_add_u64 v[2:3], s[2:3], 0, v[16:17]
	v_lshl_add_u64 v[4:5], s[4:5], 0, v[16:17]
	v_lshl_add_u64 v[6:7], s[6:7], 0, v[16:17]
	v_lshl_add_u64 v[8:9], s[8:9], 0, v[16:17]
	flat_load_dword v18, v[2:3]
	flat_load_dword v19, v[4:5]
	flat_load_dword v20, v[6:7]
	flat_load_dword v21, v[8:9]
	v_and_b32_e32 v2, 64, v183
	v_xor_b32_e32 v3, 1, v183
	v_add_u32_e32 v2, 64, v2
	v_cmp_lt_i32_e32 vcc, v3, v2
	v_xor_b32_e32 v4, 2, v183
	v_xor_b32_e32 v5, 4, v183
	v_cndmask_b32_e32 v3, v183, v3, vcc
	v_lshlrev_b32_e32 v9, 2, v3
	v_cmp_lt_i32_e32 vcc, v4, v2
	v_xor_b32_e32 v6, 8, v183
	v_xor_b32_e32 v7, 16, v183
	v_cndmask_b32_e32 v4, v183, v4, vcc
	v_lshlrev_b32_e32 v4, 2, v4
	v_cmp_lt_i32_e32 vcc, v5, v2
	v_xor_b32_e32 v8, 32, v183
	v_readfirstlane_b32 s5, v1
	v_cndmask_b32_e32 v5, v183, v5, vcc
	v_lshlrev_b32_e32 v5, 2, v5
	v_cmp_lt_i32_e32 vcc, v6, v2
	v_readfirstlane_b32 s3, v15
	v_readfirstlane_b32 s2, v14
	v_cndmask_b32_e32 v6, v183, v6, vcc
	v_lshlrev_b32_e32 v6, 2, v6
	v_cmp_lt_i32_e32 vcc, v7, v2
	v_readfirstlane_b32 s4, v0
	v_readfirstlane_b32 s85, v11
	v_cndmask_b32_e32 v7, v183, v7, vcc
	v_lshlrev_b32_e32 v7, 2, v7
	v_cmp_lt_i32_e32 vcc, v8, v2
	v_readfirstlane_b32 s84, v10
	s_waitcnt vmcnt(0) lgkmcnt(0)
	v_mul_f32_e32 v3, v18, v19
	ds_bpermute_b32 v3, v9, v3
	v_mul_f32_e32 v22, v20, v21
	ds_bpermute_b32 v22, v9, v22
	v_cndmask_b32_e32 v2, v183, v8, vcc
	v_lshlrev_b32_e32 v8, 2, v2
	s_waitcnt lgkmcnt(1)
	v_fmac_f32_e32 v3, v18, v19
	ds_bpermute_b32 v18, v4, v3
	s_waitcnt lgkmcnt(1)
	v_fmac_f32_e32 v22, v20, v21
	ds_bpermute_b32 v19, v4, v22
	s_waitcnt lgkmcnt(1)
	v_add_f32_e32 v3, v3, v18
	s_waitcnt lgkmcnt(0)
	v_add_f32_e32 v18, v22, v19
	ds_bpermute_b32 v19, v5, v3
	ds_bpermute_b32 v20, v5, v18
	s_waitcnt lgkmcnt(1)
	v_add_f32_e32 v3, v3, v19
	s_waitcnt lgkmcnt(0)
	v_add_f32_e32 v18, v18, v20
	ds_bpermute_b32 v19, v6, v3
	ds_bpermute_b32 v20, v6, v18
	s_waitcnt lgkmcnt(1)
	v_add_f32_e32 v3, v3, v19
	s_waitcnt lgkmcnt(0)
	v_add_f32_e32 v18, v18, v20
	ds_bpermute_b32 v19, v7, v3
	ds_bpermute_b32 v20, v7, v18
	s_waitcnt lgkmcnt(1)
	v_add_f32_e32 v2, v3, v19
	s_waitcnt lgkmcnt(0)
	v_add_f32_e32 v3, v18, v20
	ds_bpermute_b32 v18, v8, v2
	ds_bpermute_b32 v19, v8, v3
	s_waitcnt lgkmcnt(1)
	v_add_f32_e32 v1, v2, v18
	s_waitcnt lgkmcnt(0)
	v_add_f32_e32 v2, v3, v19
	v_mul_f32_e32 v1, 0x3fb8aa3b, v1
	v_mul_f32_e32 v2, 0x3fb8aa3b, v2
	v_exp_f32_e32 v14, v1
	v_exp_f32_e32 v15, v2
	v_lshl_add_u64 v[0:1], s[2:3], 0, v[16:17]
	v_lshl_add_u64 v[2:3], s[4:5], 0, v[16:17]
	v_readfirstlane_b32 s2, v13
	v_sub_f32_e32 v14, v14, v15
	v_add_f32_e32 v14, 0x3e4ccccd, v14
	flat_load_dword v15, v[0:1]
	flat_load_dword v16, v[2:3]
	v_writelane_b32 v254, s2, 23
	v_readfirstlane_b32 s2, v12
	v_readfirstlane_b32 s28, v14
	s_waitcnt vmcnt(0) lgkmcnt(0)
	v_and_b32_e32 v0, 0x7fffffff, v15
	v_and_b32_e32 v1, 0x7fffffff, v16
	ds_bpermute_b32 v0, v9, v0
	ds_bpermute_b32 v1, v9, v1
	v_max_f32_e64 v2, |v15|, |v15|
	v_max_f32_e64 v3, |v16|, |v16|
	v_writelane_b32 v254, s2, 24
	s_waitcnt lgkmcnt(1)
	v_max_f32_e32 v0, v0, v0
	s_waitcnt lgkmcnt(0)
	v_max_f32_e32 v1, v1, v1
	v_max_f32_e32 v0, v2, v0
	v_max_f32_e32 v1, v3, v1
	ds_bpermute_b32 v2, v4, v0
	ds_bpermute_b32 v3, v4, v1
	s_waitcnt lgkmcnt(1)
	v_max_f32_e32 v2, v2, v2
	s_waitcnt lgkmcnt(0)
	v_max_f32_e32 v3, v3, v3
	v_max_f32_e32 v0, v0, v2
	v_max_f32_e32 v1, v1, v3
	ds_bpermute_b32 v2, v5, v0
	ds_bpermute_b32 v3, v5, v1
	s_waitcnt lgkmcnt(1)
	v_max_f32_e32 v2, v2, v2
	s_waitcnt lgkmcnt(0)
	v_max_f32_e32 v3, v3, v3
	v_max_f32_e32 v0, v0, v2
	v_max_f32_e32 v1, v1, v3
	ds_bpermute_b32 v2, v6, v0
	ds_bpermute_b32 v3, v6, v1
	s_waitcnt lgkmcnt(1)
	v_max_f32_e32 v2, v2, v2
	s_waitcnt lgkmcnt(0)
	v_max_f32_e32 v3, v3, v3
	v_max_f32_e32 v0, v0, v2
	v_max_f32_e32 v1, v1, v3
	ds_bpermute_b32 v2, v7, v0
	ds_bpermute_b32 v3, v7, v1
	s_waitcnt lgkmcnt(1)
	v_max_f32_e32 v2, v2, v2
	s_waitcnt lgkmcnt(0)
	v_max_f32_e32 v3, v3, v3
	v_max_f32_e32 v0, v0, v2
	v_max_f32_e32 v1, v1, v3
	ds_bpermute_b32 v2, v8, v0
	ds_bpermute_b32 v3, v8, v1
	s_waitcnt lgkmcnt(1)
	v_max_f32_e32 v2, v2, v2
	s_waitcnt lgkmcnt(0)
	v_max_f32_e32 v3, v3, v3
	v_max_f32_e32 v0, v0, v2
	v_max_f32_e32 v1, v1, v3
	v_mul_f32_e32 v0, 0x4138aa3b, v0
	v_mul_f32_e32 v0, v0, v1
	s_nop 0
	v_readfirstlane_b32 s2, v0
	s_cbranch_scc1 .LBB0_653
; __global__ void __launch_bounds__(NWAVES * 64, 2) fwd(Args args) {
;     ...
;         for (int pi = vcu; pi < 256; pi += G) {
;             const int bh = pi >> 3, tp = pi & 7, b = bh >> 3, h = bh & 7;
;             attn_item<true>(lds, Z, MIX, b, h, 15 - tp, lam, shift, subln, 0, wid, 0);
;             ret_pair(lds, Z, MIX, b, h, 15 - tp, tp, ret_gn + 128 * h, wid);
;             attn_item<true>(lds, Z, MIX, b, h, tp, lam, shift, subln, 0, wid, 0);
;         }
	s_add_u32 s30, s0, 0x5300000
	s_addc_u32 s31, s1, 0
	s_add_u32 s88, s0, 0x2f00000
	s_addc_u32 s89, s1, 0
	s_lshl_b32 s29, s60, 4
	s_lshl_b32 s34, s60, 3
	s_lshl_b32 s35, s60, 2
	s_add_i32 s90, s33, 0
	v_sub_f32_e64 v0, 0, s2
	s_add_u32 s2, s0, 0x54c2800
	v_writelane_b32 v254, s2, 25
	s_addc_u32 s2, s1, 0
	v_writelane_b32 v254, s2, 26
	s_lshl_b32 s2, s95, 5
	s_lshl_b32 s3, s78, 5
	v_writelane_b32 v254, s3, 27
	s_add_u32 s3, s0, 0x54c0800
	v_writelane_b32 v254, s3, 28
	s_addc_u32 s3, s1, 0
	v_writelane_b32 v254, s3, 29
	s_add_u32 s0, s0, 0x54c0400
	v_writelane_b32 v254, s0, 30
	s_addc_u32 s0, s1, 0
	v_writelane_b32 v254, s0, 31
	v_writelane_b32 v254, s78, 32
	v_writelane_b32 v254, s66, 33
	v_writelane_b32 v254, s84, 34
	s_add_i32 s17, s90, 0x2000
	s_add_i32 s38, s90, 0x6000
	v_writelane_b32 v254, s85, 35
	v_writelane_b32 v254, s28, 36
	v_writelane_b32 v254, s30, 37
	s_add_i32 s39, s90, 0x8000
	s_add_i32 s18, s90, 0xa000
	v_writelane_b32 v254, s31, 38
	v_writelane_b32 v254, s88, 39
	s_add_i32 s40, s90, 0xc000
	s_add_i32 s41, s90, 0xe000
	v_writelane_b32 v254, s89, 40
	v_writelane_b32 v254, s29, 41
	v_writelane_b32 v254, s34, 42
	v_writelane_b32 v254, s35, 43
	v_writelane_b32 v254, s17, 44
	v_writelane_b32 v254, s38, 45
	v_writelane_b32 v254, s39, 46
	v_writelane_b32 v254, s18, 47
	v_writelane_b32 v254, s40, 48
	s_add_i32 s43, s90, 0x4000
	v_writelane_b32 v254, s41, 49
	v_mov_b32_e32 v1, v0
	v_mov_b32_e32 v2, v0
	v_mov_b32_e32 v3, v0
	s_movk_i32 s36, 0x3800
	s_mov_b64 s[14:15], 0x1800
	s_movk_i32 s16, 0x1000
	s_movk_i32 s37, 0x1c00
	s_mov_b64 s[96:97], 0x80
	s_movk_i32 s67, 0xe0
	s_movk_i32 s73, 0x60
	s_movk_i32 s74, 0x80
	s_movk_i32 s75, 0xa0
	s_movk_i32 s79, 0xc0
	s_mov_b64 s[92:93], 0x3000
	s_mov_b32 s42, 0x800000
	v_mov_b32_e32 v186, 0xe0
	s_mov_b32 s44, s95
	s_mov_b32 s101, 0
	s_mov_b32 s98, 0
	s_mov_b32 s99, 0x01234567
	v_writelane_b32 v254, s43, 50
	s_branch .LBB0_565
.Lp2_item_done:
	v_readlane_b32 s17, v254, 44
	v_readlane_b32 s38, v254, 45
	v_readlane_b32 s39, v254, 46
	v_readlane_b32 s18, v254, 47
	v_readlane_b32 s40, v254, 48
	v_readlane_b32 s41, v254, 49
	v_readlane_b32 s43, v254, 50
	v_readlane_b32 s28, v254, 36
	v_readlane_b32 s30, v254, 37
	v_readlane_b32 s31, v254, 38
	v_readlane_b32 s88, v254, 39
	v_readlane_b32 s89, v254, 40
	v_readlane_b32 s29, v254, 41
	v_readlane_b32 s34, v254, 42
	v_readlane_b32 s35, v254, 43
	v_readlane_b32 s66, v254, 33
	v_readlane_b32 s84, v254, 34
	v_readlane_b32 s85, v254, 35
	v_readlane_b32 s78, v254, 32
	s_mov_b32 s27, 0
	s_movk_i32 s36, 0x3800
	s_mov_b64 s[14:15], 0x1800
	s_movk_i32 s16, 0x1000
	s_movk_i32 s37, 0x1c00
	s_mov_b64 s[96:97], 0x80
	s_movk_i32 s67, 0xe0
	s_movk_i32 s73, 0x60
	s_movk_i32 s74, 0x80
	s_movk_i32 s75, 0xa0
	s_movk_i32 s79, 0xc0
	s_mov_b64 s[92:93], 0x3000
	s_mov_b32 s42, 0x800000
	v_readlane_b32 s2, v254, 51
	v_readlane_b32 s0, v254, 27
	s_mov_b32 s98, 0
	s_mov_b32 s99, 0x01234567
	s_add_i32 s95, s95, s78
	s_add_i32 s2, s2, s0
	s_add_i32 s44, s44, s78
	s_cmpk_gt_i32 s95, 0xff
	s_cbranch_scc1 .LBB0_653

; __device__ __forceinline__ int lane_id() { return (int)__builtin_amdgcn_mbcnt_hi(~0u, __builtin_amdgcn_mbcnt_lo(~0u, 0u)); }
; __device__ __forceinline__ void ret_pair(LAS unsigned char* lds, const bf16_t* Z, bf16_t* MIX, int b, int h, int tA, int tB, const float* gain, int wid) {
;     ...
;     int lf = lane_id(); asm volatile("" : "+v"(lf)); const int q16f = lf & 15, quadf = (lf >> 4) & 3;
; #pragma unroll
;     for (int which = 0; which < 2; ++which) {
;         f32x4 (&O)[8] = which ? OB : OA;
;         float ss = 0.f;
; #pragma unroll
;         for (int eb = 0; eb < 8; ++eb)
; #pragma unroll
;             for (int i = 0; i < 4; ++i) ss += O[eb][i] * O[eb][i];
;         ss = quad_sum(ss);
;         const float r = rsqrtf(ss * (1.0f / 128.0f) + EPS);
;         const int row = (which ? rowB0 : rowA0) + q16f;
;         const bf16_t* gp = Z + (size_t)row * DIN + gcol + 4 * quadf;
;         bf16_t* op = MIX + (size_t)row * DM + 128 * h + 4 * quadf;
.LBB0_640:
	s_lshl_b32 s0, s80, 2
	v_readlane_b32 s1, v254, 24
	s_add_u32 s0, s1, s0
	v_readlane_b32 s1, v254, 23
	v_readlane_b32 s2, v255, 3
	s_waitcnt lgkmcnt(0)
	v_mov_b32_e32 v4, v183
	s_addc_u32 s1, s1, 0
	s_add_i32 s4, s2, 1
	s_add_u32 s2, s30, s86
	v_and_b32_e32 v93, 15, v4
	v_lshrrev_b32_e32 v4, 2, v4
	s_addc_u32 s3, s31, 0
	v_and_b32_e32 v4, 12, v4
	v_lshlrev_b32_e32 v180, 1, v4
	v_lshlrev_b32_e32 v4, 2, v4
	v_mov_b32_e32 v5, v181
	v_or_b32_e32 v32, s5, v93
	v_mov_b64_e32 v[6:7], s[2:3]
	v_lshl_add_u64 v[4:5], s[0:1], 0, v[4:5]
	v_readlane_b32 s3, v255, 7
	s_mov_b64 s[6:7], 0x1000
	v_mad_i64_i32 v[8:9], vcc, v32, s36, v[6:7]
	v_mov_b32_e32 v29, v181
	v_or_b32_e32 v30, s3, v93
	v_lshl_add_u64 v[10:11], v[8:9], 0, v[180:181]
	v_mad_i64_i32 v[6:7], vcc, v30, s36, v[6:7]
	v_lshl_add_u64 v[10:11], v[10:11], 0, s[6:7]
	v_lshl_add_u64 v[6:7], v[6:7], 0, v[180:181]
	s_add_u32 s0, s88, s86
	s_addc_u32 s1, s89, 0
	v_lshl_add_u64 v[6:7], v[6:7], 0, s[6:7]
	global_load_dwordx4 v[96:99], v[4:5], off
	global_load_dwordx2 v[134:135], v[10:11], off
	global_load_dwordx2 v[150:151], v[6:7], off
	global_load_dwordx4 v[100:103], v[4:5], off offset:64
	global_load_dwordx2 v[136:137], v[10:11], off offset:32
	global_load_dwordx2 v[152:153], v[6:7], off offset:32
	global_load_dwordx4 v[104:107], v[4:5], off offset:128
	global_load_dwordx2 v[138:139], v[10:11], off offset:64
	global_load_dwordx2 v[154:155], v[6:7], off offset:64
	global_load_dwordx4 v[108:111], v[4:5], off offset:192
	global_load_dwordx2 v[140:141], v[10:11], off offset:96
	global_load_dwordx2 v[156:157], v[6:7], off offset:96
	global_load_dwordx4 v[112:115], v[4:5], off offset:256
	global_load_dwordx2 v[142:143], v[10:11], off offset:128
	global_load_dwordx2 v[158:159], v[6:7], off offset:128
	global_load_dwordx4 v[116:119], v[4:5], off offset:320
	global_load_dwordx2 v[144:145], v[10:11], off offset:160
	global_load_dwordx2 v[160:161], v[6:7], off offset:160
	global_load_dwordx4 v[120:123], v[4:5], off offset:384
	global_load_dwordx2 v[146:147], v[10:11], off offset:192
	global_load_dwordx2 v[162:163], v[6:7], off offset:192
	global_load_dwordx4 v[124:127], v[4:5], off offset:448
	global_load_dwordx2 v[148:149], v[10:11], off offset:224
	global_load_dwordx2 v[164:165], v[6:7], off offset:224
	v_lshl_add_u64 v[8:9], s[0:1], 0, v[180:181]
	v_mov_b32_e32 v28, v32
	v_mov_b32_e32 v31, v181
	v_lshlrev_b64 v[28:29], 12, v[28:29]
	v_lshlrev_b64 v[30:31], 12, v[30:31]
	v_lshl_add_u64 v[166:167], v[8:9], 0, v[28:29]
	v_lshl_add_u64 v[168:169], v[8:9], 0, v[30:31]
	v_mul_f32_e32 v33, v81, v81
	v_fmac_f32_e32 v33, v80, v80
	v_fmac_f32_e32 v33, v82, v82
	v_fmac_f32_e32 v33, v83, v83
	v_fmac_f32_e32 v33, v76, v76
	v_fmac_f32_e32 v33, v77, v77
	v_fmac_f32_e32 v33, v78, v78
	v_fmac_f32_e32 v33, v79, v79
	v_fmac_f32_e32 v33, v72, v72
	v_fmac_f32_e32 v33, v73, v73
	v_fmac_f32_e32 v33, v74, v74
	v_fmac_f32_e32 v33, v75, v75
	v_fmac_f32_e32 v33, v68, v68
	v_fmac_f32_e32 v33, v69, v69
	v_fmac_f32_e32 v33, v70, v70
	v_fmac_f32_e32 v33, v71, v71
	v_fmac_f32_e32 v33, v64, v64
	v_fmac_f32_e32 v33, v65, v65
	v_fmac_f32_e32 v33, v66, v66
	v_fmac_f32_e32 v33, v67, v67
	v_fmac_f32_e32 v33, v60, v60
	v_fmac_f32_e32 v33, v61, v61
	v_fmac_f32_e32 v33, v62, v62
	v_fmac_f32_e32 v33, v63, v63
	v_pk_mul_f32 v[84:85], v[56:57], v[56:57]
	v_pk_mul_f32 v[8:9], v[58:59], v[58:59]
	v_add_f32_e32 v33, v84, v33
	v_add_f32_e32 v33, v85, v33
	v_add_f32_e32 v8, v8, v33
	v_add_f32_e32 v33, v9, v8
	v_pk_mul_f32 v[84:85], v[52:53], v[52:53]
	v_pk_mul_f32 v[8:9], v[54:55], v[54:55]
	v_add_f32_e32 v33, v84, v33
	v_add_f32_e32 v33, v85, v33
	v_add_f32_e32 v8, v8, v33
	v_add_f32_e32 v33, v9, v8
	ds_swizzle_b32 v84, v33 offset:swizzle(SWAP,16)
	v_pk_mul_f32 v[90:91], v[16:17], v[16:17]
	v_pk_mul_f32 v[88:89], v[18:19], v[18:19]
	s_waitcnt lgkmcnt(0)
	v_add_f32_e32 v85, v33, v84
	v_mul_f32_e32 v84, v49, v49
	v_fmac_f32_e32 v84, v48, v48
	v_fmac_f32_e32 v84, v50, v50
	v_fmac_f32_e32 v84, v51, v51
	v_fmac_f32_e32 v84, v44, v44
	v_fmac_f32_e32 v84, v45, v45
	v_fmac_f32_e32 v84, v46, v46
	v_fmac_f32_e32 v84, v47, v47
	v_fmac_f32_e32 v84, v40, v40
	v_fmac_f32_e32 v84, v41, v41
	v_fmac_f32_e32 v84, v42, v42
	v_fmac_f32_e32 v84, v43, v43
	v_fmac_f32_e32 v84, v36, v36
	v_fmac_f32_e32 v84, v37, v37
	v_fmac_f32_e32 v84, v38, v38
	v_fmac_f32_e32 v84, v39, v39
	v_fmac_f32_e32 v84, v24, v24
	v_fmac_f32_e32 v84, v25, v25
	v_fmac_f32_e32 v84, v26, v26
	v_fmac_f32_e32 v84, v27, v27
	v_fmac_f32_e32 v84, v20, v20
	v_fmac_f32_e32 v84, v21, v21
	v_fmac_f32_e32 v84, v22, v22
	v_fmac_f32_e32 v84, v23, v23
	v_add_f32_e32 v84, v90, v84
	v_add_f32_e32 v84, v91, v84
	v_add_f32_e32 v84, v88, v84
	v_add_f32_e32 v84, v89, v84
	v_pk_mul_f32 v[90:91], v[12:13], v[12:13]
	v_pk_mul_f32 v[88:89], v[14:15], v[14:15]
	v_add_f32_e32 v84, v90, v84
	v_add_f32_e32 v84, v91, v84
	v_add_f32_e32 v84, v88, v84
	v_add_f32_e32 v84, v89, v84
	ds_swizzle_b32 v86, v84 offset:swizzle(SWAP,16)
	v_mov_b32_e32 v87, v85
	s_nop 1
	v_permlane32_swap_b32_e32 v85, v87
	s_waitcnt lgkmcnt(0)
	v_add_f32_e32 v84, v84, v86
	v_mov_b32_e32 v86, v84
	s_nop 1
	v_permlane32_swap_b32_e32 v84, v86
	v_pk_add_f32 v[84:85], v[84:85], v[86:87]
	s_brev_b32 s0, 60
	v_mov_b32_e32 v34, 0x358637bd
	v_pk_fma_f32 v[84:85], v[84:85], s[0:1], v[34:35] op_sel_hi:[1,0,0]
	s_mov_b32 s2, 0x800000
	v_mul_f32_e32 v34, 0x4b800000, v85
	v_cmp_gt_f32_e32 vcc, s2, v85
	v_mul_f32_e32 v35, 0x4b800000, v84
	v_cmp_gt_f32_e64 s[0:1], s2, v84
	v_cndmask_b32_e32 v34, v85, v34, vcc
	v_rsq_f32_e32 v85, v34
	v_cndmask_b32_e64 v35, v84, v35, s[0:1]
	v_rsq_f32_e32 v84, v35
	v_mul_f32_e32 v92, 0x45800000, v85
	v_cndmask_b32_e32 v92, v85, v92, vcc
	v_mul_f32_e32 v94, 0x45800000, v84
	v_cndmask_b32_e64 v94, v84, v94, s[0:1]
	s_mov_b32 s87, s27
	s_mov_b32 m0, s90
	s_mov_b32 s42, 0x800000
	s_mov_b32 s5, 0
	s_waitcnt vmcnt(0)
; __device__ __forceinline__ unsigned cvtpk(float lo, float hi) { f32x2 v = {lo, hi}; bf16x2_t b = __builtin_convertvector(v, bf16x2_t); return __builtin_bit_cast(unsigned, b); }
; __device__ __forceinline__ float bflo(unsigned u) { return __uint_as_float(u << 16); }
; __device__ __forceinline__ float bfhi(unsigned u) { return __uint_as_float(u & 0xffff0000u); }
; __device__ __forceinline__ void ret_pair(LAS unsigned char* lds, const bf16_t* Z, bf16_t* MIX, int b, int h, int tA, int tB, const float* gain, int wid) {
;     ...
; #pragma unroll
;         for (int eb = 0; eb < 8; ++eb) {
;             const u32x2 gw = *(const u32x2*)(gp + 16 * eb);
;             const f32x4 gn = *(const f32x4*)(gain + 16 * eb + 4 * quadf);
;             u32x2 w; w.x = cvtpk(O[eb][0] * r * gn.x * bflo(gw.x), O[eb][1] * r * gn.y * bfhi(gw.x));
;             w.y = cvtpk(O[eb][2] * r * gn.z * bflo(gw.y), O[eb][3] * r * gn.w * bfhi(gw.y));
;             *(u32x2*)(op + 16 * eb) = w;
;         }
	v_pk_mul_f32 v[80:81], v[80:81], v[92:93] op_sel_hi:[1,0]
	v_pk_mul_f32 v[82:83], v[82:83], v[92:93] op_sel_hi:[1,0]
	v_lshlrev_b32_e32 v28, 16, v134
	v_and_b32_e32 v29, 0xffff0000, v134
	v_lshlrev_b32_e32 v30, 16, v135
	v_and_b32_e32 v31, 0xffff0000, v135
	v_pk_mul_f32 v[80:81], v[96:97], v[80:81]
	v_pk_mul_f32 v[82:83], v[98:99], v[82:83]
	v_pk_mul_f32 v[80:81], v[80:81], v[28:29]
	v_pk_mul_f32 v[82:83], v[82:83], v[30:31]
	v_cvt_pk_bf16_f32 v80, v80, v81
	v_cvt_pk_bf16_f32 v81, v82, v83
	global_store_dwordx2 v[166:167], v[80:81], off
	v_pk_mul_f32 v[48:49], v[48:49], v[94:95] op_sel_hi:[1,0]
	v_pk_mul_f32 v[50:51], v[50:51], v[94:95] op_sel_hi:[1,0]
	v_lshlrev_b32_e32 v170, 16, v150
	v_and_b32_e32 v171, 0xffff0000, v150
	v_lshlrev_b32_e32 v172, 16, v151
	v_and_b32_e32 v173, 0xffff0000, v151
	v_pk_mul_f32 v[48:49], v[96:97], v[48:49]
	v_pk_mul_f32 v[50:51], v[98:99], v[50:51]
	v_pk_mul_f32 v[48:49], v[48:49], v[170:171]
	v_pk_mul_f32 v[50:51], v[50:51], v[172:173]
	v_cvt_pk_bf16_f32 v48, v48, v49
	v_cvt_pk_bf16_f32 v49, v50, v51
	global_store_dwordx2 v[168:169], v[48:49], off
	v_pk_mul_f32 v[76:77], v[76:77], v[92:93] op_sel_hi:[1,0]
	v_pk_mul_f32 v[78:79], v[78:79], v[92:93] op_sel_hi:[1,0]
	v_lshlrev_b32_e32 v28, 16, v136
	v_and_b32_e32 v29, 0xffff0000, v136
	v_lshlrev_b32_e32 v30, 16, v137
	v_and_b32_e32 v31, 0xffff0000, v137
	v_pk_mul_f32 v[76:77], v[100:101], v[76:77]
	v_pk_mul_f32 v[78:79], v[102:103], v[78:79]
	v_pk_mul_f32 v[76:77], v[76:77], v[28:29]
	v_pk_mul_f32 v[78:79], v[78:79], v[30:31]
	v_cvt_pk_bf16_f32 v76, v76, v77
	v_cvt_pk_bf16_f32 v77, v78, v79
	global_store_dwordx2 v[166:167], v[76:77], off offset:32
	v_pk_mul_f32 v[44:45], v[44:45], v[94:95] op_sel_hi:[1,0]
	v_pk_mul_f32 v[46:47], v[46:47], v[94:95] op_sel_hi:[1,0]
	v_lshlrev_b32_e32 v170, 16, v152
	v_and_b32_e32 v171, 0xffff0000, v152
	v_lshlrev_b32_e32 v172, 16, v153
	v_and_b32_e32 v173, 0xffff0000, v153
	v_pk_mul_f32 v[44:45], v[100:101], v[44:45]
	v_pk_mul_f32 v[46:47], v[102:103], v[46:47]
	v_pk_mul_f32 v[44:45], v[44:45], v[170:171]
	v_pk_mul_f32 v[46:47], v[46:47], v[172:173]
	v_cvt_pk_bf16_f32 v44, v44, v45
	v_cvt_pk_bf16_f32 v45, v46, v47
	global_store_dwordx2 v[168:169], v[44:45], off offset:32
	v_pk_mul_f32 v[72:73], v[72:73], v[92:93] op_sel_hi:[1,0]
	v_pk_mul_f32 v[74:75], v[74:75], v[92:93] op_sel_hi:[1,0]
	v_lshlrev_b32_e32 v28, 16, v138
	v_and_b32_e32 v29, 0xffff0000, v138
	v_lshlrev_b32_e32 v30, 16, v139
	v_and_b32_e32 v31, 0xffff0000, v139
	v_pk_mul_f32 v[72:73], v[104:105], v[72:73]
	v_pk_mul_f32 v[74:75], v[106:107], v[74:75]
	v_pk_mul_f32 v[72:73], v[72:73], v[28:29]
	v_pk_mul_f32 v[74:75], v[74:75], v[30:31]
	v_cvt_pk_bf16_f32 v72, v72, v73
	v_cvt_pk_bf16_f32 v73, v74, v75
	global_store_dwordx2 v[166:167], v[72:73], off offset:64
	v_pk_mul_f32 v[40:41], v[40:41], v[94:95] op_sel_hi:[1,0]
	v_pk_mul_f32 v[42:43], v[42:43], v[94:95] op_sel_hi:[1,0]
	v_lshlrev_b32_e32 v170, 16, v154
	v_and_b32_e32 v171, 0xffff0000, v154
	v_lshlrev_b32_e32 v172, 16, v155
	v_and_b32_e32 v173, 0xffff0000, v155
	v_pk_mul_f32 v[40:41], v[104:105], v[40:41]
	v_pk_mul_f32 v[42:43], v[106:107], v[42:43]
	v_pk_mul_f32 v[40:41], v[40:41], v[170:171]
	v_pk_mul_f32 v[42:43], v[42:43], v[172:173]
	v_cvt_pk_bf16_f32 v40, v40, v41
	v_cvt_pk_bf16_f32 v41, v42, v43
	global_store_dwordx2 v[168:169], v[40:41], off offset:64
	v_pk_mul_f32 v[68:69], v[68:69], v[92:93] op_sel_hi:[1,0]
	v_pk_mul_f32 v[70:71], v[70:71], v[92:93] op_sel_hi:[1,0]
	v_lshlrev_b32_e32 v28, 16, v140
	v_and_b32_e32 v29, 0xffff0000, v140
	v_lshlrev_b32_e32 v30, 16, v141
	v_and_b32_e32 v31, 0xffff0000, v141
	v_pk_mul_f32 v[68:69], v[108:109], v[68:69]
	v_pk_mul_f32 v[70:71], v[110:111], v[70:71]
	v_pk_mul_f32 v[68:69], v[68:69], v[28:29]
	v_pk_mul_f32 v[70:71], v[70:71], v[30:31]
	v_cvt_pk_bf16_f32 v68, v68, v69
	v_cvt_pk_bf16_f32 v69, v70, v71
	global_store_dwordx2 v[166:167], v[68:69], off offset:96
	v_pk_mul_f32 v[36:37], v[36:37], v[94:95] op_sel_hi:[1,0]
	v_pk_mul_f32 v[38:39], v[38:39], v[94:95] op_sel_hi:[1,0]
	v_lshlrev_b32_e32 v170, 16, v156
	v_and_b32_e32 v171, 0xffff0000, v156
	v_lshlrev_b32_e32 v172, 16, v157
	v_and_b32_e32 v173, 0xffff0000, v157
	v_pk_mul_f32 v[36:37], v[108:109], v[36:37]
	v_pk_mul_f32 v[38:39], v[110:111], v[38:39]
	v_pk_mul_f32 v[36:37], v[36:37], v[170:171]
	v_pk_mul_f32 v[38:39], v[38:39], v[172:173]
	v_cvt_pk_bf16_f32 v36, v36, v37
	v_cvt_pk_bf16_f32 v37, v38, v39
	global_store_dwordx2 v[168:169], v[36:37], off offset:96
	v_pk_mul_f32 v[64:65], v[64:65], v[92:93] op_sel_hi:[1,0]
	v_pk_mul_f32 v[66:67], v[66:67], v[92:93] op_sel_hi:[1,0]
	v_lshlrev_b32_e32 v28, 16, v142
	v_and_b32_e32 v29, 0xffff0000, v142
	v_lshlrev_b32_e32 v30, 16, v143
	v_and_b32_e32 v31, 0xffff0000, v143
	v_pk_mul_f32 v[64:65], v[112:113], v[64:65]
	v_pk_mul_f32 v[66:67], v[114:115], v[66:67]
	v_pk_mul_f32 v[64:65], v[64:65], v[28:29]
	v_pk_mul_f32 v[66:67], v[66:67], v[30:31]
	v_cvt_pk_bf16_f32 v64, v64, v65
	v_cvt_pk_bf16_f32 v65, v66, v67
; __device__ __forceinline__ unsigned cvtpk(float lo, float hi) { f32x2 v = {lo, hi}; bf16x2_t b = __builtin_convertvector(v, bf16x2_t); return __builtin_bit_cast(unsigned, b); }
; __device__ __forceinline__ float bflo(unsigned u) { return __uint_as_float(u << 16); }
; __device__ __forceinline__ float bfhi(unsigned u) { return __uint_as_float(u & 0xffff0000u); }
; __device__ __forceinline__ void ret_pair(LAS unsigned char* lds, const bf16_t* Z, bf16_t* MIX, int b, int h, int tA, int tB, const float* gain, int wid) {
;     ...
; #pragma unroll
;         for (int eb = 0; eb < 8; ++eb) {
;             const u32x2 gw = *(const u32x2*)(gp + 16 * eb);
;             const f32x4 gn = *(const f32x4*)(gain + 16 * eb + 4 * quadf);
;             u32x2 w; w.x = cvtpk(O[eb][0] * r * gn.x * bflo(gw.x), O[eb][1] * r * gn.y * bfhi(gw.x));
;             w.y = cvtpk(O[eb][2] * r * gn.z * bflo(gw.y), O[eb][3] * r * gn.w * bfhi(gw.y));
;             *(u32x2*)(op + 16 * eb) = w;
;         }
;     }
; __global__ void __launch_bounds__(NWAVES * 64, 2) fwd(Args args) {
;     ...
;         for (int pi = vcu; pi < 256; pi += G) {
;             const int bh = pi >> 3, tp = pi & 7, b = bh >> 3, h = bh & 7;
;             attn_item<true>(lds, Z, MIX, b, h, 15 - tp, lam, shift, subln, 0, wid, 0);
;             ret_pair(lds, Z, MIX, b, h, 15 - tp, tp, ret_gn + 128 * h, wid);
;             attn_item<true>(lds, Z, MIX, b, h, tp, lam, shift, subln, 0, wid, 0);
	global_store_dwordx2 v[166:167], v[64:65], off offset:128
	v_pk_mul_f32 v[24:25], v[24:25], v[94:95] op_sel_hi:[1,0]
	v_pk_mul_f32 v[26:27], v[26:27], v[94:95] op_sel_hi:[1,0]
	v_lshlrev_b32_e32 v170, 16, v158
	v_and_b32_e32 v171, 0xffff0000, v158
	v_lshlrev_b32_e32 v172, 16, v159
	v_and_b32_e32 v173, 0xffff0000, v159
	v_pk_mul_f32 v[24:25], v[112:113], v[24:25]
	v_pk_mul_f32 v[26:27], v[114:115], v[26:27]
	v_pk_mul_f32 v[24:25], v[24:25], v[170:171]
	v_pk_mul_f32 v[26:27], v[26:27], v[172:173]
	v_cvt_pk_bf16_f32 v24, v24, v25
	v_cvt_pk_bf16_f32 v25, v26, v27
	global_store_dwordx2 v[168:169], v[24:25], off offset:128
	v_pk_mul_f32 v[60:61], v[60:61], v[92:93] op_sel_hi:[1,0]
	v_pk_mul_f32 v[62:63], v[62:63], v[92:93] op_sel_hi:[1,0]
	v_lshlrev_b32_e32 v28, 16, v144
	v_and_b32_e32 v29, 0xffff0000, v144
	v_lshlrev_b32_e32 v30, 16, v145
	v_and_b32_e32 v31, 0xffff0000, v145
	v_pk_mul_f32 v[60:61], v[116:117], v[60:61]
	v_pk_mul_f32 v[62:63], v[118:119], v[62:63]
	v_pk_mul_f32 v[60:61], v[60:61], v[28:29]
	v_pk_mul_f32 v[62:63], v[62:63], v[30:31]
	v_cvt_pk_bf16_f32 v60, v60, v61
	v_cvt_pk_bf16_f32 v61, v62, v63
	global_store_dwordx2 v[166:167], v[60:61], off offset:160
	v_pk_mul_f32 v[20:21], v[20:21], v[94:95] op_sel_hi:[1,0]
	v_pk_mul_f32 v[22:23], v[22:23], v[94:95] op_sel_hi:[1,0]
	v_lshlrev_b32_e32 v170, 16, v160
	v_and_b32_e32 v171, 0xffff0000, v160
	v_lshlrev_b32_e32 v172, 16, v161
	v_and_b32_e32 v173, 0xffff0000, v161
	v_pk_mul_f32 v[20:21], v[116:117], v[20:21]
	v_pk_mul_f32 v[22:23], v[118:119], v[22:23]
	v_pk_mul_f32 v[20:21], v[20:21], v[170:171]
	v_pk_mul_f32 v[22:23], v[22:23], v[172:173]
	v_cvt_pk_bf16_f32 v20, v20, v21
	v_cvt_pk_bf16_f32 v21, v22, v23
	global_store_dwordx2 v[168:169], v[20:21], off offset:160
	v_pk_mul_f32 v[56:57], v[56:57], v[92:93] op_sel_hi:[1,0]
	v_pk_mul_f32 v[58:59], v[58:59], v[92:93] op_sel_hi:[1,0]
	v_lshlrev_b32_e32 v28, 16, v146
	v_and_b32_e32 v29, 0xffff0000, v146
	v_lshlrev_b32_e32 v30, 16, v147
	v_and_b32_e32 v31, 0xffff0000, v147
	v_pk_mul_f32 v[56:57], v[120:121], v[56:57]
	v_pk_mul_f32 v[58:59], v[122:123], v[58:59]
	v_pk_mul_f32 v[56:57], v[56:57], v[28:29]
	v_pk_mul_f32 v[58:59], v[58:59], v[30:31]
	v_cvt_pk_bf16_f32 v56, v56, v57
	v_cvt_pk_bf16_f32 v57, v58, v59
	global_store_dwordx2 v[166:167], v[56:57], off offset:192
	v_pk_mul_f32 v[16:17], v[16:17], v[94:95] op_sel_hi:[1,0]
	v_pk_mul_f32 v[18:19], v[18:19], v[94:95] op_sel_hi:[1,0]
	v_lshlrev_b32_e32 v170, 16, v162
	v_and_b32_e32 v171, 0xffff0000, v162
	v_lshlrev_b32_e32 v172, 16, v163
	v_and_b32_e32 v173, 0xffff0000, v163
	v_pk_mul_f32 v[16:17], v[120:121], v[16:17]
	v_pk_mul_f32 v[18:19], v[122:123], v[18:19]
	v_pk_mul_f32 v[16:17], v[16:17], v[170:171]
	v_pk_mul_f32 v[18:19], v[18:19], v[172:173]
	v_cvt_pk_bf16_f32 v16, v16, v17
	v_cvt_pk_bf16_f32 v17, v18, v19
	global_store_dwordx2 v[168:169], v[16:17], off offset:192
	v_pk_mul_f32 v[52:53], v[52:53], v[92:93] op_sel_hi:[1,0]
	v_pk_mul_f32 v[54:55], v[54:55], v[92:93] op_sel_hi:[1,0]
	v_lshlrev_b32_e32 v28, 16, v148
	v_and_b32_e32 v29, 0xffff0000, v148
	v_lshlrev_b32_e32 v30, 16, v149
	v_and_b32_e32 v31, 0xffff0000, v149
	v_pk_mul_f32 v[52:53], v[124:125], v[52:53]
	v_pk_mul_f32 v[54:55], v[126:127], v[54:55]
	v_pk_mul_f32 v[52:53], v[52:53], v[28:29]
	v_pk_mul_f32 v[54:55], v[54:55], v[30:31]
	v_cvt_pk_bf16_f32 v52, v52, v53
	v_cvt_pk_bf16_f32 v53, v54, v55
	global_store_dwordx2 v[166:167], v[52:53], off offset:224
	v_pk_mul_f32 v[12:13], v[12:13], v[94:95] op_sel_hi:[1,0]
	v_pk_mul_f32 v[14:15], v[14:15], v[94:95] op_sel_hi:[1,0]
	v_lshlrev_b32_e32 v170, 16, v164
	v_and_b32_e32 v171, 0xffff0000, v164
	v_lshlrev_b32_e32 v172, 16, v165
	v_and_b32_e32 v173, 0xffff0000, v165
	v_pk_mul_f32 v[12:13], v[124:125], v[12:13]
	v_pk_mul_f32 v[14:15], v[126:127], v[14:15]
	v_pk_mul_f32 v[12:13], v[12:13], v[170:171]
	v_pk_mul_f32 v[14:15], v[14:15], v[172:173]
	v_cvt_pk_bf16_f32 v12, v12, v13
	v_cvt_pk_bf16_f32 v13, v14, v15
	global_store_dwordx2 v[168:169], v[12:13], off offset:224
	v_readlane_b32 s17, v254, 44
	v_readlane_b32 s38, v254, 45
	v_readlane_b32 s39, v254, 46
	v_readlane_b32 s18, v254, 47
	v_readlane_b32 s40, v254, 48
	v_readlane_b32 s41, v254, 49
	v_readlane_b32 s43, v254, 50
	v_readlane_b32 s28, v254, 36
	v_readlane_b32 s30, v254, 37
	v_readlane_b32 s31, v254, 38
	v_readlane_b32 s88, v254, 39
	v_readlane_b32 s89, v254, 40
	v_readlane_b32 s29, v254, 41
	v_readlane_b32 s34, v254, 42
	v_readlane_b32 s35, v254, 43
	v_readlane_b32 s66, v254, 33
	v_readlane_b32 s84, v254, 34
	v_readlane_b32 s85, v254, 35
	v_readlane_b32 s78, v254, 32
	s_mov_b32 s27, 0
	s_movk_i32 s36, 0x3800
	s_mov_b64 s[14:15], 0x1800
	s_movk_i32 s16, 0x1000
	s_movk_i32 s37, 0x1c00
	s_mov_b64 s[96:97], 0x80
	s_movk_i32 s67, 0xe0
	s_movk_i32 s73, 0x60
	s_movk_i32 s74, 0x80
	s_movk_i32 s75, 0xa0
	s_movk_i32 s79, 0xc0
	s_mov_b64 s[92:93], 0x3000
	s_mov_b32 s42, 0x800000
	v_readlane_b32 s44, v255, 2
	v_readlane_b32 s2, v254, 51
	s_mov_b32 s98, 1
	s_mov_b32 s99, 0x89abcdef
	s_branch .LBB0_565
